# G3: the idle-half CUs convert weights first and then run their five units (offset from the six-unit CUs)
# speedup vs baseline: 1.0034x; 1.0007x over previous
.LBB0_853:
	s_mov_b32 s97, 0
	s_andn2_b64 vcc, exec, s[0:1]
	s_cbranch_vccnz .LBB0_979
.Lg3_setup:
	v_readlane_b32 s0, v252, 0
	v_readlane_b32 s1, v252, 1
	s_load_dwordx2 s[8:9], s[0:1], 0xd8
	v_readlane_b32 s4, v254, 5
	v_mov_b32_e32 v12, v0
	v_readlane_b32 s5, v254, 6
	s_mov_b32 s70, s26
	s_mul_i32 s10, s26, 0x1800000
	s_andn2_b64 vcc, exec, s[4:5]
	v_readfirstlane_b32 s26, v12
	s_cbranch_vccnz .LBB0_870
	s_cmp_lg_u32 s97, 0
	s_cbranch_scc1 .Lg3_gemm
	v_readlane_b32 s82, v255, 62
	v_readlane_b32 s83, v252, 5
	s_nop 3
	s_cmp_eq_u32 s82, 0
	s_cbranch_scc1 .Lg3_gemm
	s_cmp_lt_u32 s83, 128
	s_cbranch_scc1 .Lg3_gemm
	s_mov_b32 s97, 1
	s_branch .LBB0_870
.Lg3_gemm:
	v_lshlrev_b32_e32 v1, 4, v12
	v_add_u32_e32 v2, 0x2000, v1
	v_ashrrev_i32_e32 v4, 31, v2
	v_lshrrev_b32_e32 v4, 22, v4
	v_add_u32_e32 v4, v2, v4
	s_waitcnt lgkmcnt(0)
	v_ashrrev_i32_e32 v13, 10, v4
	v_mul_i32_i24_e32 v4, 0x400, v13
	v_sub_u32_e32 v2, v2, v4
	v_lshrrev_b32_e32 v4, 4, v2
	v_bitop3_b32 v2, v4, v2, 32 bitop3:0x6c
	v_ashrrev_i32_e32 v4, 31, v2
	s_add_u32 s11, s8, 0x3200000
	v_lshrrev_b32_e32 v4, 26, v4
	s_addc_u32 s14, s9, 0
	v_add_u32_e32 v4, v2, v4
	v_lshlrev_b32_e32 v5, 3, v13
	s_add_u32 s4, s8, s10
	v_ashrrev_i32_e32 v14, 6, v4
	v_and_b32_e32 v5, -16, v5
	s_addc_u32 s5, s9, 0
	v_add_u32_e32 v5, v14, v5
	s_add_u32 s15, s4, 0x900000
	v_and_b32_e32 v6, 3, v14
	s_mov_b32 s4, 0x1fffe0
	v_lshrrev_b32_e32 v7, 2, v5
	v_lshlrev_b32_e32 v8, 1, v5
	v_and_b32_e32 v4, 0xc0, v4
	v_and_or_b32 v6, v5, s4, v6
	v_and_b32_e32 v7, 4, v7
	v_and_b32_e32 v8, 24, v8
	v_sub_u32_e32 v2, v2, v4
	v_or3_b32 v6, v6, v7, v8
	v_lshlrev_b32_e32 v7, 5, v13
	v_ashrrev_i16_sdwa v2, v217, sext(v2) dst_sel:DWORD dst_unused:UNUSED_PAD src0_sel:DWORD src1_sel:BYTE_0
	v_and_b32_e32 v7, 32, v7
	v_bfe_i32 v15, v2, 0, 16
	v_add_lshl_u32 v2, v7, v15, 1
	v_lshl_add_u32 v136, v6, 11, v2
	v_lshl_add_u32 v138, v5, 11, v2
	v_bfe_i32 v2, v12, 27, 1
	v_lshrrev_b32_e32 v2, 22, v2
	v_add_u32_e32 v2, v1, v2
	v_and_b32_e32 v2, 0xfffffc00, v2
	v_sub_u32_e32 v1, v1, v2
	v_lshrrev_b32_e32 v2, 4, v1
	v_ashrrev_i32_e32 v4, 31, v12
	v_bitop3_b32 v1, v2, v1, 32 bitop3:0x6c
	v_lshrrev_b32_e32 v4, 26, v4
	v_ashrrev_i32_e32 v2, 31, v1
	v_add_u32_e32 v4, v12, v4
	v_lshrrev_b32_e32 v2, 26, v2
	v_ashrrev_i32_e32 v17, 6, v4
	v_add_u32_e32 v2, v1, v2
	v_lshlrev_b32_e32 v4, 3, v17
	v_ashrrev_i32_e32 v16, 6, v2
	v_and_b32_e32 v4, -16, v4
	v_add_u32_e32 v4, v16, v4
	v_and_b32_e32 v5, 3, v16
	v_lshrrev_b32_e32 v6, 2, v4
	v_lshlrev_b32_e32 v7, 1, v4
	v_and_b32_e32 v2, 0xc0, v2
	s_addc_u32 s50, s5, 0
	s_ashr_i32 s28, s26, 6
	v_and_or_b32 v5, v4, s4, v5
	v_and_b32_e32 v6, 4, v6
	v_and_b32_e32 v7, 24, v7
	v_sub_u32_e32 v1, v1, v2
	s_ashr_i32 s27, s26, 8
	s_lshl_b32 s51, s28, 10
	v_or3_b32 v5, v5, v6, v7
	v_lshlrev_b32_e32 v6, 5, v17
	v_ashrrev_i16_sdwa v1, v217, sext(v1) dst_sel:DWORD dst_unused:UNUSED_PAD src0_sel:DWORD src1_sel:BYTE_0
	v_readlane_b32 s4, v254, 15
	v_and_b32_e32 v6, 32, v6
	v_bfe_i32 v18, v1, 0, 16
	v_readlane_b32 s5, v254, 16
	s_add_u32 s18, s15, s4
	v_add_lshl_u32 v1, v6, v18, 1
	s_addc_u32 s19, s50, s5
	s_add_i32 s52, s51, 0
	v_lshl_add_u32 v2, v5, 11, v1
	s_add_i32 m0, s52, 0x10000
	v_lshl_add_u32 v140, v4, 11, v1
	global_load_lds_dwordx4 v2, s[18:19]
	s_add_i32 m0, s52, 0x12000
	s_add_u32 s4, s18, 0x40000
	global_load_lds_dwordx4 v136, s[18:19]
	s_addc_u32 s5, s19, 0
	s_add_i32 m0, s52, 0x14000
	v_mov_b32_e32 v137, v3
	global_load_lds_dwordx4 v2, s[4:5]
	s_add_i32 m0, s52, 0x16000
	v_mov_b32_e32 v141, v3
	global_load_lds_dwordx4 v136, s[4:5]
	v_readlane_b32 s4, v254, 28
	v_readlane_b32 s5, v254, 29
	s_add_u32 s4, s11, s4
	s_addc_u32 s5, s14, s5
	s_add_i32 s53, s52, 0x2000
	s_mov_b32 m0, s52
	s_add_u32 s6, s4, 0x40000
	global_load_lds_dwordx4 v140, s[4:5]
	s_mov_b32 m0, s53
	s_addc_u32 s7, s5, 0
	s_add_i32 s54, s52, 0x4000
	global_load_lds_dwordx4 v138, s[4:5]
	s_mov_b32 m0, s54
	s_add_i32 s55, s52, 0x6000
	global_load_lds_dwordx4 v140, s[6:7]
	s_mov_b32 m0, s55
	v_mov_b32_e32 v139, v3
	global_load_lds_dwordx4 v138, s[6:7]
	s_cmp_eq_u32 s27, 1
	v_lshl_add_u64 v[10:11], s[18:19], 0, v[2:3]
	v_lshl_add_u64 v[8:9], s[18:19], 0, v[136:137]
	v_lshl_add_u64 v[4:5], s[4:5], 0, v[140:141]
	s_cselect_b64 s[6:7], -1, 0
	s_cmp_lg_u32 s27, 1
	v_lshl_add_u64 v[6:7], s[4:5], 0, v[138:139]
	s_cbranch_scc1 .LBB0_857
	s_barrier

.LBB0_870:
	s_cmp_eq_u32 s97, 2
	s_cbranch_scc0 .Lg3_conv_go
	s_mov_b32 s97, 0
	s_mov_b32 s26, s70
	s_branch .LBB0_925

.LBB0_925:
	s_cmp_eq_u32 s97, 1
	s_cbranch_scc0 .Lg3_end
	s_mov_b32 s97, 2
	s_waitcnt vmcnt(0) lgkmcnt(0)
	s_barrier
	s_branch .Lg3_setup
